# XCD barrier moved from after the SwiGLU context tiles to before them: the down-projection starts one tile time earlier on workgroups with a single context tile, de-phasing their residual epilogues
# speedup vs baseline: 1.0011x; 1.0011x over previous
; DI void grid_barrier(unsigned* cnt, unsigned target) {
;     asm volatile("s_waitcnt vmcnt(0) lgkmcnt(0)" ::: "memory");
;     __syncthreads();
;     if (threadIdx.x == 0) {
;         __builtin_amdgcn_fence(__ATOMIC_RELEASE, "agent");
;         asm volatile("s_waitcnt vmcnt(0)" ::: "memory");
;         __hip_atomic_fetch_add(cnt, 1u, __ATOMIC_RELAXED, __HIP_MEMORY_SCOPE_AGENT);
;         while (__hip_atomic_load(cnt, __ATOMIC_RELAXED, __HIP_MEMORY_SCOPE_AGENT) < target) __builtin_amdgcn_s_sleep(2);
;         __builtin_amdgcn_fence(__ATOMIC_ACQUIRE, "agent");
;         asm volatile("s_waitcnt vmcnt(0)" ::: "memory");
;     }
;     __syncthreads();
; }
.Lch_not2:
	s_cmp_eq_u32 s98, 3
	s_cbranch_scc0 .Lch_not3
	s_waitcnt vmcnt(0) lgkmcnt(0)
	s_barrier
	v_readlane_b32 s10, v255, 60
	s_add_u32 s10, s10, 1
	s_nop 0
	v_writelane_b32 v255, s10, 60
	s_lshl_b32 s10, s10, 5
	v_readlane_b32 s2, v255, 0
	s_mov_b64 s[4:5], exec
	v_readlane_b32 s6, v255, 3
	v_readlane_b32 s7, v255, 4
	s_and_b64 s[6:7], s[4:5], s[6:7]
	s_mov_b64 exec, s[6:7]
	s_cbranch_execz .Llb_S
	s_and_b32 s3, s2, 7
	s_lshl_b32 s3, s3, 2
	s_add_u32 s8, s14, s3
	s_addc_u32 s9, s15, 0
	v_mov_b32_e32 v0, 1
	global_atomic_add v1, v0, s[8:9] offset:128

; DI void grid_barrier(unsigned* cnt, unsigned target) {
;     asm volatile("s_waitcnt vmcnt(0) lgkmcnt(0)" ::: "memory");
;     __syncthreads();
;     if (threadIdx.x == 0) {
;         __builtin_amdgcn_fence(__ATOMIC_RELEASE, "agent");
;         asm volatile("s_waitcnt vmcnt(0)" ::: "memory");
;         __hip_atomic_fetch_add(cnt, 1u, __ATOMIC_RELAXED, __HIP_MEMORY_SCOPE_AGENT);
;         while (__hip_atomic_load(cnt, __ATOMIC_RELAXED, __HIP_MEMORY_SCOPE_AGENT) < target) __builtin_amdgcn_s_sleep(2);
;         __builtin_amdgcn_fence(__ATOMIC_ACQUIRE, "agent");
;         asm volatile("s_waitcnt vmcnt(0)" ::: "memory");
;     }
;     __syncthreads();
; }
.Lli_S:
.Llb_S:
	s_mov_b64 exec, s[4:5]
	s_barrier
	v_readlane_b32 s10, v255, 61
	s_lshl_b32 s10, s10, 8
	s_mov_b64 s[4:5], exec
	v_readlane_b32 s6, v255, 3
	v_readlane_b32 s7, v255, 4
	s_and_b64 s[6:7], s[4:5], s[6:7]
	s_mov_b64 exec, s[6:7]
	s_cbranch_execz .Lwd_C

; DI void grid_barrier(unsigned* cnt, unsigned target) {
;     asm volatile("s_waitcnt vmcnt(0) lgkmcnt(0)" ::: "memory");
;     __syncthreads();
;     if (threadIdx.x == 0) {
;         __builtin_amdgcn_fence(__ATOMIC_RELEASE, "agent");
;         asm volatile("s_waitcnt vmcnt(0)" ::: "memory");
;         __hip_atomic_fetch_add(cnt, 1u, __ATOMIC_RELAXED, __HIP_MEMORY_SCOPE_AGENT);
;         while (__hip_atomic_load(cnt, __ATOMIC_RELAXED, __HIP_MEMORY_SCOPE_AGENT) < target) __builtin_amdgcn_s_sleep(2);
;         __builtin_amdgcn_fence(__ATOMIC_ACQUIRE, "agent");
;         asm volatile("s_waitcnt vmcnt(0)" ::: "memory");
;     }
;     __syncthreads();
; }
.Lar_D:
	s_mov_b64 exec, s[4:5]
	s_mov_b32 s98, 5
	s_branch .LBB0_585
